# LayerNorm passes: 64-lane butterfly sums via permlane32/16 swap and DPP row/quad permutes instead of 24 ds_bpermute round trips per trip (same xor order, bit-identical)
# speedup vs baseline: 1.0048x; 1.0010x over previous
; DI float wave_sum(float v) {
; #pragma unroll
;     for (int o = 32; o >= 1; o >>= 1) v += __shfl_xor(v, o);
;     return v;
; }
;     ...
;     for (int row = vb * 8 + w; row < TT; row += 2 * stride) {
;         const int row2 = row + stride; const bool has2 = row2 < TT;
;         const f32x4* xr = (const f32x4*)(X32 + (size_t)row * DM); const f32x4* xr2 = (const f32x4*)(X32 + (size_t)(has2 ? row2 : row) * DM);
;         f32x4 v[4], u[4]; float s = 0.f, t = 0.f;
; #pragma unroll
;         for (int j = 0; j < 4; ++j) { v[j] = xr[l + 64 * j]; u[j] = xr2[l + 64 * j]; }
; #pragma unroll
;         for (int j = 0; j < 4; ++j) { s += (v[j].x + v[j].y) + (v[j].z + v[j].w); t += (u[j].x + u[j].y) + (u[j].z + u[j].w); }
;         const float mean = wave_sum(s) * (1.f / DM), mean2 = wave_sum(t) * (1.f / DM); float s2 = 0.f, t2 = 0.f;
; #pragma unroll
;         for (int j = 0; j < 4; ++j) { v[j] = v[j] - mean; u[j] = u[j] - mean2; s2 += (v[j].x * v[j].x + v[j].y * v[j].y) + (v[j].z * v[j].z + v[j].w * v[j].w); t2 += (u[j].x * u[j].x + u[j].y * u[j].y) + (u[j].z * u[j].z + u[j].w * u[j].w); }
;         const float rstd = __builtin_amdgcn_rsqf(wave_sum(s2) * (1.f / DM) + EPS), rstd2 = __builtin_amdgcn_rsqf(wave_sum(t2) * (1.f / DM) + EPS);
.LBB0_1112:
	v_ashrrev_i32_e32 v71, 31, v70
	v_lshlrev_b64 v[34:35], 12, v[70:71]
	v_lshl_add_u64 v[44:45], v[64:65], 0, v[34:35]
	v_add_u32_e32 v68, s31, v70
	s_mov_b32 s0, 0x8000
	global_load_dwordx4 v[60:63], v[44:45], off
	v_cmp_gt_i32_e64 s[0:1], s0, v68
	v_cndmask_b32_e64 v32, v70, v68, s[0:1]
	v_ashrrev_i32_e32 v33, 31, v32
	v_lshlrev_b64 v[32:33], 12, v[32:33]
	v_lshl_add_u64 v[46:47], v[64:65], 0, v[32:33]
	global_load_dwordx4 v[40:43], v[46:47], off
	global_load_dwordx4 v[56:59], v[44:45], off offset:1024
	global_load_dwordx4 v[36:39], v[46:47], off offset:1024
	global_load_dwordx4 v[52:55], v[44:45], off offset:2048
	global_load_dwordx4 v[32:35], v[46:47], off offset:2048
	global_load_dwordx4 v[48:51], v[44:45], off offset:3072
	s_nop 0
	global_load_dwordx4 v[44:47], v[46:47], off offset:3072
	s_waitcnt lgkmcnt(0)
	s_waitcnt vmcnt(7)
	v_mov_b32_e32 v80, v61
	v_mov_b32_e32 v81, v62
	v_mov_b32_e32 v82, v60
	v_mov_b32_e32 v83, v63
	v_pk_add_f32 v[80:81], v[80:81], v[82:83]
	s_waitcnt vmcnt(6)
	v_mov_b32_e32 v82, v41
	v_mov_b32_e32 v83, v42
	v_mov_b32_e32 v84, v40
	v_mov_b32_e32 v85, v43
	v_pk_add_f32 v[82:83], v[82:83], v[84:85]
	s_waitcnt vmcnt(5)
	v_mov_b32_e32 v84, v57
	v_mov_b32_e32 v85, v58
	v_mov_b32_e32 v86, v56
	v_mov_b32_e32 v87, v59
	v_pk_add_f32 v[84:85], v[84:85], v[86:87]
	v_add_f32_e32 v69, v80, v81
	v_pk_add_f32 v[84:85], v[84:85], v[84:85] op_sel:[0,1] op_sel_hi:[1,0]
	s_waitcnt vmcnt(4)
	v_mov_b32_e32 v86, v37
	v_mov_b32_e32 v87, v38
	v_mov_b32_e32 v88, v36
	v_mov_b32_e32 v89, v39
	v_add_f32_e32 v80, 0, v69
	v_pk_add_f32 v[86:87], v[86:87], v[88:89]
	s_waitcnt vmcnt(3)
	v_add_f32_e32 v88, v52, v53
	v_add_f32_e32 v90, v54, v55
	s_waitcnt vmcnt(1)
	v_mov_b32_e32 v81, v48
	v_mov_b32_e32 v85, v49
	v_mov_b32_e32 v89, v50
	v_mov_b32_e32 v91, v51
	v_pk_add_f32 v[80:81], v[80:81], v[84:85]
	v_pk_add_f32 v[84:85], v[88:89], v[90:91]
	v_add_f32_e32 v69, v82, v83
	v_pk_add_f32 v[80:81], v[80:81], v[84:85]
	v_add_f32_e32 v82, 0, v69
	v_add_f32_e32 v69, v80, v81
	v_pk_add_f32 v[86:87], v[86:87], v[86:87] op_sel:[0,1] op_sel_hi:[1,0]
	v_add_f32_e32 v92, v32, v33
	v_add_f32_e32 v94, v34, v35
	s_waitcnt vmcnt(0)
	v_mov_b32_e32 v83, v44
	s_waitcnt lgkmcnt(0)
	v_mov_b32_e32 v79, v69
	s_nop 1
	v_permlane32_swap_b32_e32 v69, v79
	v_add_f32_e32 v69, v69, v79
	v_mov_b32_e32 v87, v45
	v_mov_b32_e32 v93, v46
	v_mov_b32_e32 v95, v47
	v_pk_add_f32 v[80:81], v[82:83], v[86:87]
	s_waitcnt lgkmcnt(0)
	v_mov_b32_e32 v79, v69
	s_nop 1
	v_permlane16_swap_b32_e32 v69, v79
	v_add_f32_e32 v69, v69, v79
	s_nop 1
	v_mov_b32_dpp v79, v69 row_ror:8 row_mask:0xf bank_mask:0xf
	v_pk_add_f32 v[82:83], v[92:93], v[94:95]
	s_waitcnt lgkmcnt(0)
	v_add_f32_e32 v69, v69, v79
	s_nop 1
	v_mov_b32_dpp v79, v69 row_shl:4 row_mask:0xf bank_mask:0x5
	v_mov_b32_dpp v79, v69 row_shr:4 row_mask:0xf bank_mask:0xa
	v_pk_add_f32 v[80:81], v[80:81], v[82:83]
	s_waitcnt lgkmcnt(0)
	v_add_f32_e32 v69, v69, v79
	s_nop 1
	v_mov_b32_dpp v79, v69 quad_perm:[2,3,0,1] row_mask:0xf bank_mask:0xf
	v_add_f32_e32 v72, v80, v81
	s_waitcnt lgkmcnt(0)
	v_add_f32_e32 v69, v69, v79
	s_nop 1
	v_mov_b32_dpp v79, v69 quad_perm:[1,0,3,2] row_mask:0xf bank_mask:0xf
	s_waitcnt lgkmcnt(0)
	v_add_f32_e32 v69, v69, v79
	v_fmamk_f32 v62, v69, 0xba800000, v62
	v_fmamk_f32 v61, v69, 0xba800000, v61
	v_fmamk_f32 v63, v69, 0xba800000, v63
	v_fmac_f32_e32 v60, 0xba800000, v69
	s_waitcnt lgkmcnt(0)
	v_mov_b32_e32 v79, v72
	s_nop 1
	v_permlane32_swap_b32_e32 v72, v79
	v_add_f32_e32 v72, v72, v79
	v_mul_f32_e32 v80, v62, v62
	v_fmac_f32_e32 v80, v63, v63
	v_fmamk_f32 v58, v69, 0xba800000, v58
	v_fmamk_f32 v57, v69, 0xba800000, v57
	s_waitcnt lgkmcnt(0)
	v_mov_b32_e32 v79, v72
	s_nop 1
	v_permlane16_swap_b32_e32 v72, v79
	v_add_f32_e32 v72, v72, v79
	s_nop 1
	v_mov_b32_dpp v79, v72 row_ror:8 row_mask:0xf bank_mask:0xf
	v_fmamk_f32 v59, v69, 0xba800000, v59
	v_fmac_f32_e32 v56, 0xba800000, v69
	v_mul_f32_e32 v82, v58, v58
	v_fmac_f32_e32 v82, v59, v59
	s_waitcnt lgkmcnt(0)
	v_add_f32_e32 v72, v72, v79
	s_nop 1
	v_mov_b32_dpp v79, v72 row_shl:4 row_mask:0xf bank_mask:0x5
	v_mov_b32_dpp v79, v72 row_shr:4 row_mask:0xf bank_mask:0xa
	v_fmamk_f32 v54, v69, 0xba800000, v54
	v_fmamk_f32 v53, v69, 0xba800000, v53
	v_fmamk_f32 v55, v69, 0xba800000, v55
	v_fmac_f32_e32 v52, 0xba800000, v69
	s_waitcnt lgkmcnt(0)
; DI u32x2 pk4(float a, float b, float c, float d) { u32x2 r; r.x = pk2(a, b); r.y = pk2(c, d); return r; }
;     ...
;         for (int j = 0; j < 4; ++j) { s += (v[j].x + v[j].y) + (v[j].z + v[j].w); t += (u[j].x + u[j].y) + (u[j].z + u[j].w); }
;         const float mean = wave_sum(s) * (1.f / DM), mean2 = wave_sum(t) * (1.f / DM); float s2 = 0.f, t2 = 0.f;
; #pragma unroll
;         for (int j = 0; j < 4; ++j) { v[j] = v[j] - mean; u[j] = u[j] - mean2; s2 += (v[j].x * v[j].x + v[j].y * v[j].y) + (v[j].z * v[j].z + v[j].w * v[j].w); t2 += (u[j].x * u[j].x + u[j].y * u[j].y) + (u[j].z * u[j].z + u[j].w * u[j].w); }
;         const float rstd = __builtin_amdgcn_rsqf(wave_sum(s2) * (1.f / DM) + EPS), rstd2 = __builtin_amdgcn_rsqf(wave_sum(t2) * (1.f / DM) + EPS);
;         if (!dry) {
;             u32x2* xb = (u32x2*)(Xb + (size_t)row * DM);
;             if (l == 0) STATS[row] = (f32x2){mean, rstd};
; #pragma unroll
;             for (int j = 0; j < 4; ++j) { f32x4 o = v[j] * rstd * gg[j] + bb[j]; xb[l + 64 * j] = pk4(o.x, o.y, o.z, o.w); }
	v_add_f32_e32 v72, v72, v79
	s_nop 1
	v_mov_b32_dpp v79, v72 quad_perm:[2,3,0,1] row_mask:0xf bank_mask:0xf
	v_fmamk_f32 v50, v69, 0xba800000, v50
	v_fmamk_f32 v49, v69, 0xba800000, v49
	v_fmamk_f32 v51, v69, 0xba800000, v51
	v_fmac_f32_e32 v48, 0xba800000, v69
	s_waitcnt lgkmcnt(0)
	v_add_f32_e32 v72, v72, v79
	s_nop 1
	v_mov_b32_dpp v79, v72 quad_perm:[1,0,3,2] row_mask:0xf bank_mask:0xf
	s_waitcnt lgkmcnt(0)
	v_add_f32_e32 v79, v72, v79
	v_mul_f32_e32 v72, v61, v61
	v_fmamk_f32 v43, v79, 0xba800000, v43
	v_fmamk_f32 v41, v79, 0xba800000, v41
	v_fmac_f32_e32 v72, v60, v60
	v_fmamk_f32 v42, v79, 0xba800000, v42
	v_fmac_f32_e32 v40, 0xba800000, v79
	v_add_f32_e32 v72, v72, v80
	v_mul_f32_e32 v80, v41, v41
	v_mul_f32_e32 v81, v43, v43
	v_fmac_f32_e32 v80, v40, v40
	v_fmac_f32_e32 v81, v42, v42
	v_add_f32_e32 v80, v80, v81
	v_mul_f32_e32 v81, v57, v57
	v_fmac_f32_e32 v81, v56, v56
	v_fmamk_f32 v39, v79, 0xba800000, v39
	v_fmamk_f32 v37, v79, 0xba800000, v37
	v_add_f32_e32 v81, v81, v82
	v_fmamk_f32 v38, v79, 0xba800000, v38
	v_fmac_f32_e32 v36, 0xba800000, v79
	v_add_f32_e32 v72, v72, v81
	v_mul_f32_e32 v81, v37, v37
	v_mul_f32_e32 v82, v39, v39
	v_fmac_f32_e32 v81, v36, v36
	v_fmac_f32_e32 v82, v38, v38
	v_add_f32_e32 v81, v81, v82
	v_add_f32_e32 v80, v80, v81
	v_mul_f32_e32 v81, v53, v53
	v_mul_f32_e32 v82, v54, v54
	v_fmac_f32_e32 v81, v52, v52
	v_fmac_f32_e32 v82, v55, v55
	v_fmamk_f32 v35, v79, 0xba800000, v35
	v_fmamk_f32 v33, v79, 0xba800000, v33
	v_add_f32_e32 v81, v81, v82
	v_fmamk_f32 v34, v79, 0xba800000, v34
	v_fmac_f32_e32 v32, 0xba800000, v79
	v_add_f32_e32 v72, v81, v72
	v_mul_f32_e32 v81, v33, v33
	v_mul_f32_e32 v82, v35, v35
	v_fmac_f32_e32 v81, v32, v32
	v_fmac_f32_e32 v82, v34, v34
	v_add_f32_e32 v81, v81, v82
	v_add_f32_e32 v80, v81, v80
	v_mul_f32_e32 v81, v49, v49
	v_mul_f32_e32 v82, v50, v50
	v_fmac_f32_e32 v81, v48, v48
	v_fmac_f32_e32 v82, v51, v51
	v_fmamk_f32 v47, v79, 0xba800000, v47
	v_fmamk_f32 v45, v79, 0xba800000, v45
	v_add_f32_e32 v81, v81, v82
	v_fmamk_f32 v46, v79, 0xba800000, v46
	v_fmac_f32_e32 v44, 0xba800000, v79
	v_add_f32_e32 v72, v81, v72
	v_mul_f32_e32 v81, v45, v45
	v_mul_f32_e32 v82, v47, v47
	v_fmac_f32_e32 v81, v44, v44
	v_fmac_f32_e32 v82, v46, v46
	v_add_f32_e32 v81, v81, v82
	v_add_f32_e32 v80, v81, v80
	s_waitcnt lgkmcnt(0)
	v_mov_b32_e32 v81, v72
	s_nop 1
	v_permlane32_swap_b32_e32 v72, v81
	v_add_f32_e32 v72, v72, v81
	s_waitcnt lgkmcnt(0)
	v_mov_b32_e32 v81, v72
	s_nop 1
	v_permlane16_swap_b32_e32 v72, v81
	v_add_f32_e32 v72, v72, v81
	s_nop 1
	v_mov_b32_dpp v81, v72 row_ror:8 row_mask:0xf bank_mask:0xf
	s_waitcnt lgkmcnt(0)
	v_add_f32_e32 v72, v72, v81
	s_nop 1
	v_mov_b32_dpp v81, v72 row_shl:4 row_mask:0xf bank_mask:0x5
	v_mov_b32_dpp v81, v72 row_shr:4 row_mask:0xf bank_mask:0xa
	s_waitcnt lgkmcnt(0)
	v_add_f32_e32 v72, v72, v81
	s_nop 1
	v_mov_b32_dpp v81, v72 quad_perm:[2,3,0,1] row_mask:0xf bank_mask:0xf
	s_waitcnt lgkmcnt(0)
	v_add_f32_e32 v72, v72, v81
	s_nop 1
	v_mov_b32_dpp v81, v72 quad_perm:[1,0,3,2] row_mask:0xf bank_mask:0xf
	s_waitcnt lgkmcnt(0)
	v_add_f32_e32 v72, v72, v81
	v_fmamk_f32 v72, v72, 0x3a800000, v252
	v_rsq_f32_e32 v72, v72
	s_waitcnt lgkmcnt(0)
	v_mov_b32_e32 v81, v80
	s_nop 1
	v_permlane32_swap_b32_e32 v80, v81
	v_add_f32_e32 v80, v80, v81
	s_waitcnt lgkmcnt(0)
	v_mov_b32_e32 v81, v80
	s_nop 1
	v_permlane16_swap_b32_e32 v80, v81
	v_add_f32_e32 v80, v80, v81
	s_nop 1
	v_mov_b32_dpp v81, v80 row_ror:8 row_mask:0xf bank_mask:0xf
	s_waitcnt lgkmcnt(0)
	v_add_f32_e32 v80, v80, v81
	s_nop 1
	v_mov_b32_dpp v81, v80 row_shl:4 row_mask:0xf bank_mask:0x5
	v_mov_b32_dpp v81, v80 row_shr:4 row_mask:0xf bank_mask:0xa
	s_waitcnt lgkmcnt(0)
	v_add_f32_e32 v80, v80, v81
	s_nop 1
	v_mov_b32_dpp v81, v80 quad_perm:[2,3,0,1] row_mask:0xf bank_mask:0xf
	s_waitcnt lgkmcnt(0)
	v_add_f32_e32 v80, v80, v81
	s_nop 1
	v_mov_b32_dpp v81, v80 quad_perm:[1,0,3,2] row_mask:0xf bank_mask:0xf
	s_and_saveexec_b64 s[18:19], vcc
	s_cbranch_execz .LBB0_1114
	v_readlane_b32 s20, v254, 46
	v_readlane_b32 s21, v254, 47
	v_mul_f32_e32 v82, 0x3a800000, v69
	v_mov_b32_e32 v83, v72
	v_lshl_add_u64 v[84:85], v[70:71], 3, s[20:21]
	global_store_dwordx2 v[84:85], v[82:83], off

; DI float wave_sum(float v) {
; #pragma unroll
;     for (int o = 32; o >= 1; o >>= 1) v += __shfl_xor(v, o);
;     return v;
; }
;     ...
;     for (int row = vb * 8 + w; row < TT; row += 2 * stride) {
;         const int row2 = row + stride; const bool has2 = row2 < TT;
;         const f32x4* xr = (const f32x4*)(X32 + (size_t)row * DM); const f32x4* xr2 = (const f32x4*)(X32 + (size_t)(has2 ? row2 : row) * DM);
;         f32x4 v[4], u[4]; float s = 0.f, t = 0.f;
; #pragma unroll
;         for (int j = 0; j < 4; ++j) { v[j] = xr[l + 64 * j]; u[j] = xr2[l + 64 * j]; }
; #pragma unroll
;         for (int j = 0; j < 4; ++j) { s += (v[j].x + v[j].y) + (v[j].z + v[j].w); t += (u[j].x + u[j].y) + (u[j].z + u[j].w); }
;         const float mean = wave_sum(s) * (1.f / DM), mean2 = wave_sum(t) * (1.f / DM); float s2 = 0.f, t2 = 0.f;
; #pragma unroll
;         for (int j = 0; j < 4; ++j) { v[j] = v[j] - mean; u[j] = u[j] - mean2; s2 += (v[j].x * v[j].x + v[j].y * v[j].y) + (v[j].z * v[j].z + v[j].w * v[j].w); t2 += (u[j].x * u[j].x + u[j].y * u[j].y) + (u[j].z * u[j].z + u[j].w * u[j].w); }
;         const float rstd = __builtin_amdgcn_rsqf(wave_sum(s2) * (1.f / DM) + EPS), rstd2 = __builtin_amdgcn_rsqf(wave_sum(t2) * (1.f / DM) + EPS);
.LBB0_1827:
	v_ashrrev_i32_e32 v71, 31, v70
	v_lshlrev_b64 v[34:35], 12, v[70:71]
	v_lshl_add_u64 v[44:45], v[64:65], 0, v[34:35]
	v_add_u32_e32 v68, s31, v70
	s_mov_b32 s0, 0x8000
	global_load_dwordx4 v[60:63], v[44:45], off
	v_cmp_gt_i32_e64 s[0:1], s0, v68
	v_cndmask_b32_e64 v32, v70, v68, s[0:1]
	v_ashrrev_i32_e32 v33, 31, v32
	v_lshlrev_b64 v[32:33], 12, v[32:33]
	v_lshl_add_u64 v[46:47], v[64:65], 0, v[32:33]
	global_load_dwordx4 v[40:43], v[46:47], off
	global_load_dwordx4 v[56:59], v[44:45], off offset:1024
	global_load_dwordx4 v[36:39], v[46:47], off offset:1024
	global_load_dwordx4 v[52:55], v[44:45], off offset:2048
	global_load_dwordx4 v[32:35], v[46:47], off offset:2048
	global_load_dwordx4 v[48:51], v[44:45], off offset:3072
	s_nop 0
	global_load_dwordx4 v[44:47], v[46:47], off offset:3072
	s_waitcnt lgkmcnt(0)
	s_waitcnt vmcnt(7)
	v_mov_b32_e32 v80, v61
	v_mov_b32_e32 v81, v62
	v_mov_b32_e32 v82, v60
	v_mov_b32_e32 v83, v63
	v_pk_add_f32 v[80:81], v[80:81], v[82:83]
	s_waitcnt vmcnt(6)
	v_mov_b32_e32 v82, v41
	v_mov_b32_e32 v83, v42
	v_mov_b32_e32 v84, v40
	v_mov_b32_e32 v85, v43
	v_pk_add_f32 v[82:83], v[82:83], v[84:85]
	s_waitcnt vmcnt(5)
	v_mov_b32_e32 v84, v57
	v_mov_b32_e32 v85, v58
	v_mov_b32_e32 v86, v56
	v_mov_b32_e32 v87, v59
	v_pk_add_f32 v[84:85], v[84:85], v[86:87]
	v_add_f32_e32 v69, v80, v81
	v_pk_add_f32 v[84:85], v[84:85], v[84:85] op_sel:[0,1] op_sel_hi:[1,0]
	s_waitcnt vmcnt(4)
	v_mov_b32_e32 v86, v37
	v_mov_b32_e32 v87, v38
	v_mov_b32_e32 v88, v36
	v_mov_b32_e32 v89, v39
	v_add_f32_e32 v80, 0, v69
	v_pk_add_f32 v[86:87], v[86:87], v[88:89]
	s_waitcnt vmcnt(3)
	v_add_f32_e32 v88, v52, v53
	v_add_f32_e32 v90, v54, v55
	s_waitcnt vmcnt(1)
	v_mov_b32_e32 v81, v48
	v_mov_b32_e32 v85, v49
	v_mov_b32_e32 v89, v50
	v_mov_b32_e32 v91, v51
	v_pk_add_f32 v[80:81], v[80:81], v[84:85]
	v_pk_add_f32 v[84:85], v[88:89], v[90:91]
	v_add_f32_e32 v69, v82, v83
	v_pk_add_f32 v[80:81], v[80:81], v[84:85]
	v_add_f32_e32 v82, 0, v69
	v_add_f32_e32 v69, v80, v81
	v_pk_add_f32 v[86:87], v[86:87], v[86:87] op_sel:[0,1] op_sel_hi:[1,0]
	v_add_f32_e32 v92, v32, v33
	v_add_f32_e32 v94, v34, v35
	s_waitcnt vmcnt(0)
	v_mov_b32_e32 v83, v44
	s_waitcnt lgkmcnt(0)
	v_mov_b32_e32 v79, v69
	s_nop 1
	v_permlane32_swap_b32_e32 v69, v79
	v_add_f32_e32 v69, v69, v79
	v_mov_b32_e32 v87, v45
	v_mov_b32_e32 v93, v46
	v_mov_b32_e32 v95, v47
	v_pk_add_f32 v[80:81], v[82:83], v[86:87]
	s_waitcnt lgkmcnt(0)
	v_mov_b32_e32 v79, v69
	s_nop 1
	v_permlane16_swap_b32_e32 v69, v79
	v_add_f32_e32 v69, v69, v79
	s_nop 1
	v_mov_b32_dpp v79, v69 row_ror:8 row_mask:0xf bank_mask:0xf
	v_pk_add_f32 v[82:83], v[92:93], v[94:95]
	s_waitcnt lgkmcnt(0)
	v_add_f32_e32 v69, v69, v79
	s_nop 1
	v_mov_b32_dpp v79, v69 row_shl:4 row_mask:0xf bank_mask:0x5
	v_mov_b32_dpp v79, v69 row_shr:4 row_mask:0xf bank_mask:0xa
	v_pk_add_f32 v[80:81], v[80:81], v[82:83]
	s_waitcnt lgkmcnt(0)
	v_add_f32_e32 v69, v69, v79
	s_nop 1
	v_mov_b32_dpp v79, v69 quad_perm:[2,3,0,1] row_mask:0xf bank_mask:0xf
	v_add_f32_e32 v72, v80, v81
	s_waitcnt lgkmcnt(0)
	v_add_f32_e32 v69, v69, v79
	s_nop 1
	v_mov_b32_dpp v79, v69 quad_perm:[1,0,3,2] row_mask:0xf bank_mask:0xf
	s_waitcnt lgkmcnt(0)
	v_add_f32_e32 v69, v69, v79
	v_fmamk_f32 v62, v69, 0xba800000, v62
	v_fmamk_f32 v61, v69, 0xba800000, v61
	v_fmamk_f32 v63, v69, 0xba800000, v63
	v_fmac_f32_e32 v60, 0xba800000, v69
	s_waitcnt lgkmcnt(0)
	v_mov_b32_e32 v79, v72
	s_nop 1
	v_permlane32_swap_b32_e32 v72, v79
	v_add_f32_e32 v72, v72, v79
	v_mul_f32_e32 v80, v62, v62
	v_fmac_f32_e32 v80, v63, v63
	v_fmamk_f32 v58, v69, 0xba800000, v58
	v_fmamk_f32 v57, v69, 0xba800000, v57
	s_waitcnt lgkmcnt(0)
	v_mov_b32_e32 v79, v72
	s_nop 1
	v_permlane16_swap_b32_e32 v72, v79
	v_add_f32_e32 v72, v72, v79
	s_nop 1
	v_mov_b32_dpp v79, v72 row_ror:8 row_mask:0xf bank_mask:0xf
	v_fmamk_f32 v59, v69, 0xba800000, v59
	v_fmac_f32_e32 v56, 0xba800000, v69
	v_mul_f32_e32 v82, v58, v58
	v_fmac_f32_e32 v82, v59, v59
	s_waitcnt lgkmcnt(0)
	v_add_f32_e32 v72, v72, v79
	s_nop 1
	v_mov_b32_dpp v79, v72 row_shl:4 row_mask:0xf bank_mask:0x5
	v_mov_b32_dpp v79, v72 row_shr:4 row_mask:0xf bank_mask:0xa
	v_fmamk_f32 v54, v69, 0xba800000, v54
	v_fmamk_f32 v53, v69, 0xba800000, v53
	v_fmamk_f32 v55, v69, 0xba800000, v55
	v_fmac_f32_e32 v52, 0xba800000, v69
	s_waitcnt lgkmcnt(0)
; DI u32x2 pk4(float a, float b, float c, float d) { u32x2 r; r.x = pk2(a, b); r.y = pk2(c, d); return r; }
;     ...
;         for (int j = 0; j < 4; ++j) { s += (v[j].x + v[j].y) + (v[j].z + v[j].w); t += (u[j].x + u[j].y) + (u[j].z + u[j].w); }
;         const float mean = wave_sum(s) * (1.f / DM), mean2 = wave_sum(t) * (1.f / DM); float s2 = 0.f, t2 = 0.f;
; #pragma unroll
;         for (int j = 0; j < 4; ++j) { v[j] = v[j] - mean; u[j] = u[j] - mean2; s2 += (v[j].x * v[j].x + v[j].y * v[j].y) + (v[j].z * v[j].z + v[j].w * v[j].w); t2 += (u[j].x * u[j].x + u[j].y * u[j].y) + (u[j].z * u[j].z + u[j].w * u[j].w); }
;         const float rstd = __builtin_amdgcn_rsqf(wave_sum(s2) * (1.f / DM) + EPS), rstd2 = __builtin_amdgcn_rsqf(wave_sum(t2) * (1.f / DM) + EPS);
;         if (!dry) {
;             u32x2* xb = (u32x2*)(Xb + (size_t)row * DM);
;             if (l == 0) STATS[row] = (f32x2){mean, rstd};
; #pragma unroll
;             for (int j = 0; j < 4; ++j) { f32x4 o = v[j] * rstd * gg[j] + bb[j]; xb[l + 64 * j] = pk4(o.x, o.y, o.z, o.w); }
	v_add_f32_e32 v72, v72, v79
	s_nop 1
	v_mov_b32_dpp v79, v72 quad_perm:[2,3,0,1] row_mask:0xf bank_mask:0xf
	v_fmamk_f32 v50, v69, 0xba800000, v50
	v_fmamk_f32 v49, v69, 0xba800000, v49
	v_fmamk_f32 v51, v69, 0xba800000, v51
	v_fmac_f32_e32 v48, 0xba800000, v69
	s_waitcnt lgkmcnt(0)
	v_add_f32_e32 v72, v72, v79
	s_nop 1
	v_mov_b32_dpp v79, v72 quad_perm:[1,0,3,2] row_mask:0xf bank_mask:0xf
	s_waitcnt lgkmcnt(0)
	v_add_f32_e32 v79, v72, v79
	v_mul_f32_e32 v72, v61, v61
	v_fmamk_f32 v43, v79, 0xba800000, v43
	v_fmamk_f32 v41, v79, 0xba800000, v41
	v_fmac_f32_e32 v72, v60, v60
	v_fmamk_f32 v42, v79, 0xba800000, v42
	v_fmac_f32_e32 v40, 0xba800000, v79
	v_add_f32_e32 v72, v72, v80
	v_mul_f32_e32 v80, v41, v41
	v_mul_f32_e32 v81, v43, v43
	v_fmac_f32_e32 v80, v40, v40
	v_fmac_f32_e32 v81, v42, v42
	v_add_f32_e32 v80, v80, v81
	v_mul_f32_e32 v81, v57, v57
	v_fmac_f32_e32 v81, v56, v56
	v_fmamk_f32 v39, v79, 0xba800000, v39
	v_fmamk_f32 v37, v79, 0xba800000, v37
	v_add_f32_e32 v81, v81, v82
	v_fmamk_f32 v38, v79, 0xba800000, v38
	v_fmac_f32_e32 v36, 0xba800000, v79
	v_add_f32_e32 v72, v72, v81
	v_mul_f32_e32 v81, v37, v37
	v_mul_f32_e32 v82, v39, v39
	v_fmac_f32_e32 v81, v36, v36
	v_fmac_f32_e32 v82, v38, v38
	v_add_f32_e32 v81, v81, v82
	v_add_f32_e32 v80, v80, v81
	v_mul_f32_e32 v81, v53, v53
	v_mul_f32_e32 v82, v54, v54
	v_fmac_f32_e32 v81, v52, v52
	v_fmac_f32_e32 v82, v55, v55
	v_fmamk_f32 v35, v79, 0xba800000, v35
	v_fmamk_f32 v33, v79, 0xba800000, v33
	v_add_f32_e32 v81, v81, v82
	v_fmamk_f32 v34, v79, 0xba800000, v34
	v_fmac_f32_e32 v32, 0xba800000, v79
	v_add_f32_e32 v72, v81, v72
	v_mul_f32_e32 v81, v33, v33
	v_mul_f32_e32 v82, v35, v35
	v_fmac_f32_e32 v81, v32, v32
	v_fmac_f32_e32 v82, v34, v34
	v_add_f32_e32 v81, v81, v82
	v_add_f32_e32 v80, v81, v80
	v_mul_f32_e32 v81, v49, v49
	v_mul_f32_e32 v82, v50, v50
	v_fmac_f32_e32 v81, v48, v48
	v_fmac_f32_e32 v82, v51, v51
	v_fmamk_f32 v47, v79, 0xba800000, v47
	v_fmamk_f32 v45, v79, 0xba800000, v45
	v_add_f32_e32 v81, v81, v82
	v_fmamk_f32 v46, v79, 0xba800000, v46
	v_fmac_f32_e32 v44, 0xba800000, v79
	v_add_f32_e32 v72, v81, v72
	v_mul_f32_e32 v81, v45, v45
	v_mul_f32_e32 v82, v47, v47
	v_fmac_f32_e32 v81, v44, v44
	v_fmac_f32_e32 v82, v46, v46
	v_add_f32_e32 v81, v81, v82
	v_add_f32_e32 v80, v81, v80
	s_waitcnt lgkmcnt(0)
	v_mov_b32_e32 v81, v72
	s_nop 1
	v_permlane32_swap_b32_e32 v72, v81
	v_add_f32_e32 v72, v72, v81
	s_waitcnt lgkmcnt(0)
	v_mov_b32_e32 v81, v72
	s_nop 1
	v_permlane16_swap_b32_e32 v72, v81
	v_add_f32_e32 v72, v72, v81
	s_nop 1
	v_mov_b32_dpp v81, v72 row_ror:8 row_mask:0xf bank_mask:0xf
	s_waitcnt lgkmcnt(0)
	v_add_f32_e32 v72, v72, v81
	s_nop 1
	v_mov_b32_dpp v81, v72 row_shl:4 row_mask:0xf bank_mask:0x5
	v_mov_b32_dpp v81, v72 row_shr:4 row_mask:0xf bank_mask:0xa
	s_waitcnt lgkmcnt(0)
	v_add_f32_e32 v72, v72, v81
	s_nop 1
	v_mov_b32_dpp v81, v72 quad_perm:[2,3,0,1] row_mask:0xf bank_mask:0xf
	s_waitcnt lgkmcnt(0)
	v_add_f32_e32 v72, v72, v81
	s_nop 1
	v_mov_b32_dpp v81, v72 quad_perm:[1,0,3,2] row_mask:0xf bank_mask:0xf
	s_waitcnt lgkmcnt(0)
	v_add_f32_e32 v72, v72, v81
	v_fmamk_f32 v72, v72, 0x3a800000, v252
	v_rsq_f32_e32 v72, v72
	s_waitcnt lgkmcnt(0)
	v_mov_b32_e32 v81, v80
	s_nop 1
	v_permlane32_swap_b32_e32 v80, v81
	v_add_f32_e32 v80, v80, v81
	s_waitcnt lgkmcnt(0)
	v_mov_b32_e32 v81, v80
	s_nop 1
	v_permlane16_swap_b32_e32 v80, v81
	v_add_f32_e32 v80, v80, v81
	s_nop 1
	v_mov_b32_dpp v81, v80 row_ror:8 row_mask:0xf bank_mask:0xf
	s_waitcnt lgkmcnt(0)
	v_add_f32_e32 v80, v80, v81
	s_nop 1
	v_mov_b32_dpp v81, v80 row_shl:4 row_mask:0xf bank_mask:0x5
	v_mov_b32_dpp v81, v80 row_shr:4 row_mask:0xf bank_mask:0xa
	s_waitcnt lgkmcnt(0)
	v_add_f32_e32 v80, v80, v81
	s_nop 1
	v_mov_b32_dpp v81, v80 quad_perm:[2,3,0,1] row_mask:0xf bank_mask:0xf
	s_waitcnt lgkmcnt(0)
	v_add_f32_e32 v80, v80, v81
	s_nop 1
	v_mov_b32_dpp v81, v80 quad_perm:[1,0,3,2] row_mask:0xf bank_mask:0xf
	s_and_saveexec_b64 s[20:21], vcc
	s_cbranch_execz .LBB0_1829
	v_readlane_b32 s34, v254, 46
	v_readlane_b32 s35, v254, 47
	v_mul_f32_e32 v82, 0x3a800000, v69
	v_mov_b32_e32 v83, v72
	v_lshl_add_u64 v[84:85], v[70:71], 3, s[34:35]
	global_store_dwordx2 v[84:85], v[82:83], off
